# normmod loops: modulation loads issued at loop top and kept in flight past the next-row prefetch (counted waits)
# speedup vs baseline: 1.0058x; 1.0058x over previous
; DI void phase_normmod(ArgsP a, int tb_, int l, int which, bool first, bool addp, bool ctx0, bool copyh, int MR, int vcu, int G) {
;     int tid_ = tb_ + lane_asm(); asm volatile("" : "+v"(tid_)); const int tid = tid_, lane = tid & 63, wave = tid >> 6;
;     const int gw = vcu * NWAVES + wave, NGW = G * NWAVES;
;     const float* g = (which == 0 ? a->in[I_GFFN1] : which == 1 ? a->in[I_GMIX] : a->in[I_GFFN2]) + l * D;
;     const float* mod = (const float*)(a->ws + WS_MOD) + (size_t)l * 9 * (NMOD * D);
;     float* hc = (float*)(a->ws + WS_HC); bf16_t* U = (bf16_t*)(a->ws + WS_U); const bf16_t* hb16 = (const bf16_t*)a->out; bf16_t* hcopy = (bf16_t*)(a->ws + A_HCOPY);
;     ...
;     u32x4 nraw[4];
;     if (gw < MR) NM_LOAD(gw, nraw);
;     for (int m = gw; m < MR; m += NGW) {
;         const int br = m < ML ? (m >> 12) : 8; const bool isb = !first && m < ML;
;         f32x4 v[4]; float s = 0.f; u32x4 raw[4];
; #pragma unroll
;         for (int j = 0; j < 4; ++j) raw[j] = nraw[j];
;         { const int mn = m + NGW; if (mn < MR) NM_LOAD(mn, nraw); }
;         const f32x4* gp = (const f32x4*)g + lane; const f32x4* sh = (const f32x4*)(mod + (size_t)br * (NMOD * D) + (3 * which) * D) + lane; const f32x4* scp = (const f32x4*)(mod + (size_t)br * (NMOD * D) + (3 * which + 1) * D) + lane;
;         f32x4 gv[4], sv[4], cv[4];
; #pragma unroll
;         for (int j = 0; j < 4; ++j) { gv[j] = gp[64 * j]; sv[j] = sh[64 * j]; cv[j] = scp[64 * j] + 1.f; }
; #pragma unroll
;         for (int j = 0; j < 4; ++j) { v[j] = isb ? (f32x4){bflo(raw[j].x), bfhi(raw[j].x), bflo(raw[j].y), bfhi(raw[j].y)} : __builtin_bit_cast(f32x4, raw[j]);
;             s += (v[j].x * v[j].x + v[j].y * v[j].y) + (v[j].z * v[j].z + v[j].w * v[j].w); }
;         if (copyh && isb) { u32x2* c = (u32x2*)(hcopy + (size_t)m * D) + lane;
; #pragma unroll
;             for (int j = 0; j < 4; ++j) c[64 * j] = (u32x2){raw[j].x, raw[j].y}; }
;         if (addp && m >= ML) { const f32x4* pp = (const f32x4*)((const float*)(a->ws + A_PART) + (size_t)(m - ML) * D) + lane; s = 0.f;
; #pragma unroll
;             for (int jh = 0; jh < 2; ++jh) { f32x4 pv[2][8];
; #pragma unroll
;                 for (int jj = 0; jj < 2; ++jj)
; #pragma unroll
;                     for (int p = 0; p < 8; ++p) pv[jj][p] = pp[(size_t)p * MC * (D / 4) + 64 * (2 * jh + jj)];
;                 __builtin_amdgcn_sched_barrier(0);
; #pragma unroll
.LBB0_18:
	s_or_b64 exec, exec, s[12:13]
	s_load_dwordx2 s[20:21], s[10:11], 0x30
	s_lshl_b32 s12, s35, 3
	v_lshlrev_b32_e32 v188, 4, v2
	s_add_u32 s14, s6, 0x151000
	v_lshlrev_b32_e32 v1, 2, v2
	s_waitcnt lgkmcnt(0)
	v_lshl_add_u64 v[4:5], s[20:21], 0, v[188:189]
	s_mov_b64 s[20:21], 0x1000
	s_addc_u32 s15, s7, 0
	v_lshl_add_u64 v[80:81], v[4:5], 0, s[20:21]
	v_lshl_add_u64 v[4:5], s[6:7], 0, v[188:189]
	s_mov_b64 s[20:21], 0x14a00000
	v_xor_b32_e32 v116, 4, v1
	v_xor_b32_e32 v117, 8, v1
	v_xor_b32_e32 v118, 16, v1
	v_xor_b32_e32 v119, 32, v1
	v_xor_b32_e32 v120, 64, v1
	v_xor_b32_e32 v121, 0x80, v1
	v_ashrrev_i32_e32 v1, 31, v0
	s_ashr_i32 s17, s16, 31
	s_add_i32 s2, s16, s12
	v_lshl_add_u64 v[82:83], v[4:5], 0, s[20:21]
	v_lshl_add_u64 v[4:5], v[0:1], 0, s[16:17]
	v_add_u32_e32 v0, s2, v0
	v_lshlrev_b64 v[4:5], 11, v[4:5]
	v_ashrrev_i32_e32 v1, 31, v0
	v_lshl_add_u64 v[4:5], s[6:7], 0, v[4:5]
	s_mov_b64 s[6:7], 0xa00400
	s_ashr_i32 s13, s12, 31
	v_lshlrev_b64 v[0:1], 11, v[0:1]
	v_lshl_add_u64 v[84:85], s[18:19], 0, v[188:189]
	v_lshl_add_u64 v[86:87], v[4:5], 0, s[6:7]
	v_lshlrev_b32_e32 v88, 3, v2
	v_mov_b32_e32 v89, v189
	s_lshl_b64 s[6:7], s[12:13], 11
	v_lshl_add_u64 v[90:91], s[4:5], 0, v[0:1]
	s_mov_b64 s[16:17], 0
	s_waitcnt vmcnt(0)
	s_branch .LBB0_20
.LBB0_19:
	s_or_b64 exec, exec, s[18:19]
	s_waitcnt vmcnt(5)
	v_pk_add_f32 v[74:75], v[74:75], 1.0 op_sel_hi:[1,0]
	v_pk_add_f32 v[72:73], v[72:73], 1.0 op_sel_hi:[1,0]
	v_pk_add_f32 v[62:63], v[62:63], 1.0 op_sel_hi:[1,0]
	v_pk_add_f32 v[60:61], v[60:61], 1.0 op_sel_hi:[1,0]
	v_pk_add_f32 v[58:59], v[58:59], 1.0 op_sel_hi:[1,0]
	v_pk_add_f32 v[56:57], v[56:57], 1.0 op_sel_hi:[1,0]
	s_waitcnt vmcnt(4)
	v_pk_add_f32 v[54:55], v[54:55], 1.0 op_sel_hi:[1,0]
	v_pk_add_f32 v[52:53], v[52:53], 1.0 op_sel_hi:[1,0]
	s_and_b64 s[4:5], exec, s[4:5]
	s_or_b64 s[16:17], s[4:5], s[16:17]
	v_add_f32_dpp v93, v93, v93 quad_perm:[1,0,3,2] row_mask:0xf bank_mask:0xf
	s_nop 1
	v_add_f32_dpp v93, v93, v93 quad_perm:[2,3,0,1] row_mask:0xf bank_mask:0xf
	s_nop 1
	v_add_f32_dpp v93, v93, v93 row_half_mirror row_mask:0xf bank_mask:0xf
	s_nop 1
	v_add_f32_dpp v93, v93, v93 row_mirror row_mask:0xf bank_mask:0xf
	s_nop 1
	v_add_f32_dpp v93, v93, v93 row_bcast:15 row_mask:0xa bank_mask:0xf
	s_nop 1
	v_add_f32_dpp v93, v93, v93 row_bcast:31 row_mask:0xc bank_mask:0xf
	s_nop 0
	v_readlane_b32 vcc_lo, v93, 63
	s_nop 1
	v_mov_b32_e32 v93, vcc_lo
	v_fmamk_f32 v93, v93, 0x3a800000, v230
	v_mul_f32_e32 v94, 0x4b800000, v93
	v_cmp_gt_f32_e32 vcc, s76, v93
	s_nop 1
	v_cndmask_b32_e32 v93, v93, v94, vcc
	v_rsq_f32_e32 v93, v93
	v_lshl_add_u64 v[94:95], v[86:87], 0, v[88:89]
	v_lshl_add_u64 v[88:89], v[88:89], 0, s[6:7]
	v_mul_f32_e32 v96, 0x45800000, v93
	v_cndmask_b32_e32 v96, v93, v96, vcc
	v_pk_mul_f32 v[70:71], v[70:71], v[96:97] op_sel_hi:[1,0]
	v_pk_mul_f32 v[68:69], v[68:69], v[96:97] op_sel_hi:[1,0]
	v_pk_mul_f32 v[78:79], v[78:79], v[96:97] op_sel_hi:[1,0]
	v_pk_mul_f32 v[76:77], v[76:77], v[96:97] op_sel_hi:[1,0]
	v_pk_mul_f32 v[66:67], v[66:67], v[96:97] op_sel_hi:[1,0]
	v_pk_mul_f32 v[64:65], v[64:65], v[96:97] op_sel_hi:[1,0]
	v_pk_mul_f32 v[32:33], v[32:33], v[68:69]
	v_pk_mul_f32 v[34:35], v[34:35], v[70:71]
	v_pk_mul_f32 v[28:29], v[28:29], v[76:77]
	v_pk_mul_f32 v[30:31], v[30:31], v[78:79]
	v_pk_mul_f32 v[44:45], v[44:45], v[64:65]
	v_pk_mul_f32 v[46:47], v[46:47], v[66:67]
	v_pk_fma_f32 v[34:35], v[74:75], v[34:35], v[42:43]
	v_pk_fma_f32 v[32:33], v[72:73], v[32:33], v[40:41]
	v_pk_fma_f32 v[26:27], v[62:63], v[30:31], v[26:27]
	v_pk_fma_f32 v[24:25], v[60:61], v[28:29], v[24:25]
	v_pk_fma_f32 v[38:39], v[58:59], v[46:47], v[38:39]
	v_pk_fma_f32 v[36:37], v[56:57], v[44:45], v[36:37]
	v_cvt_pk_bf16_f32 v32, v32, v33
	v_cvt_pk_bf16_f32 v33, v34, v35
	v_cvt_pk_bf16_f32 v24, v24, v25
	v_cvt_pk_bf16_f32 v25, v26, v27
	v_cvt_pk_bf16_f32 v34, v36, v37
	v_cvt_pk_bf16_f32 v35, v38, v39
	global_store_dwordx2 v[94:95], v[32:33], off offset:-1024
	global_store_dwordx2 v[94:95], v[34:35], off offset:-512
	global_store_dwordx2 v[94:95], v[24:25], off
	v_pk_mul_f32 v[24:25], v[50:51], v[96:97] op_sel_hi:[1,0]
	v_pk_mul_f32 v[26:27], v[48:49], v[96:97] op_sel_hi:[1,0]
	v_pk_mul_f32 v[22:23], v[22:23], v[24:25]
	v_pk_mul_f32 v[20:21], v[20:21], v[26:27]
	v_pk_fma_f32 v[18:19], v[54:55], v[22:23], v[18:19]
	v_pk_fma_f32 v[16:17], v[52:53], v[20:21], v[16:17]
	s_waitcnt vmcnt(3)
	v_mov_b32_e32 v68, v0
	v_cvt_pk_bf16_f32 v16, v16, v17
	v_cvt_pk_bf16_f32 v17, v18, v19
	global_store_dwordx2 v[94:95], v[16:17], off offset:512
	v_mov_b32_e32 v94, v92
	v_mov_b32_e32 v69, v1
	v_mov_b32_e32 v70, v2
	v_mov_b32_e32 v71, v3
	v_mov_b32_e32 v64, v4
	v_mov_b32_e32 v65, v5
	v_mov_b32_e32 v66, v6
	v_mov_b32_e32 v67, v7
	v_mov_b32_e32 v76, v8
	v_mov_b32_e32 v77, v9
	v_mov_b32_e32 v78, v10
	v_mov_b32_e32 v79, v11
	v_mov_b32_e32 v48, v12
	v_mov_b32_e32 v49, v13
	v_mov_b32_e32 v50, v14
	v_mov_b32_e32 v51, v15
	s_andn2_b64 exec, exec, s[16:17]
	s_cbranch_execz .LBB0_28
.LBB0_20:
	v_add_u32_e32 v95, 0x8000, v94
	v_min_i32_e32 v16, 0x8000, v95
	v_ashrrev_i32_e32 v16, 12, v16
	v_mul_hi_i32_i24_e32 v17, 0x9000, v16
	v_mul_i32_i24_e32 v16, 0x9000, v16
	v_lshl_add_u64 v[16:17], s[14:15], 0, v[16:17]
	v_lshl_add_u64 v[16:17], v[16:17], 0, v[188:189]
	s_mov_b64 s[18:19], 0x1000
	v_add_co_u32_e32 v54, vcc, s93, v16
	v_lshl_add_u64 v[52:53], v[16:17], 0, s[18:19]
	s_nop 0
	v_addc_co_u32_e32 v55, vcc, 0, v17, vcc
	global_load_dwordx4 v[32:35], v[80:81], off
	global_load_dwordx4 v[44:47], v[80:81], off offset:1024
	global_load_dwordx4 v[40:43], v[16:17], off
	global_load_dwordx4 v[36:39], v[16:17], off offset:1024
	global_load_dwordx4 v[56:59], v[52:53], off offset:1024
	global_load_dwordx4 v[60:63], v[52:53], off offset:2048
	global_load_dwordx4 v[28:31], v[80:81], off offset:2048
	global_load_dwordx4 v[20:23], v[80:81], off offset:3072
	global_load_dwordx4 v[24:27], v[16:17], off offset:2048
	s_nop 0
	global_load_dwordx4 v[16:19], v[16:17], off offset:3072
	s_nop 0
	global_load_dwordx4 v[72:75], v[54:55], off
	s_nop 0
	global_load_dwordx4 v[52:55], v[52:53], off offset:3072
	v_add_u32_e32 v92, s12, v94
	v_add_u32_e32 v200, 0x8000, v92
	v_cmp_gt_i32_e32 vcc, s63, v200
	v_cmp_lt_i32_e64 s[4:5], s70, v200
	v_mov_b32_e32 v0, v68
	v_mov_b32_e32 v1, v69
	v_mov_b32_e32 v2, v70
	v_mov_b32_e32 v3, v71
	v_mov_b32_e32 v4, v64
	v_mov_b32_e32 v5, v65
	v_mov_b32_e32 v6, v66
	v_mov_b32_e32 v7, v67
	v_mov_b32_e32 v8, v76
	v_mov_b32_e32 v9, v77
	v_mov_b32_e32 v10, v78
	v_mov_b32_e32 v11, v79
	v_mov_b32_e32 v12, v48
	v_mov_b32_e32 v13, v49
	v_mov_b32_e32 v14, v50
	v_mov_b32_e32 v15, v51
	s_and_saveexec_b64 s[18:19], vcc
	s_cbranch_execz .Lnm_skip_20
	v_cmp_gt_i32_e32 vcc, s74, v200
	s_and_saveexec_b64 s[20:21], vcc
	s_xor_b64 s[20:21], exec, s[20:21]
	s_cbranch_execz .LBB0_23
	v_lshl_add_u64 v[2:3], v[90:91], 0, v[88:89]
	global_load_dwordx2 v[0:1], v[2:3], off
	global_load_dwordx2 v[4:5], v[2:3], off offset:512
	global_load_dwordx2 v[8:9], v[2:3], off offset:1024
	global_load_dwordx2 v[12:13], v[2:3], off offset:1536

; DI void phase_normmod(ArgsP a, int tb_, int l, int which, bool first, bool addp, bool ctx0, bool copyh, int MR, int vcu, int G) {
;     ...
;     for (int m = gw; m < MR; m += NGW) {
;         const int br = m < ML ? (m >> 12) : 8; const bool isb = !first && m < ML;
;         f32x4 v[4]; float s = 0.f; u32x4 raw[4];
; #pragma unroll
;         for (int j = 0; j < 4; ++j) raw[j] = nraw[j];
;         { const int mn = m + NGW; if (mn < MR) NM_LOAD(mn, nraw); }
.LBB0_25:
	s_or_b64 exec, exec, s[20:21]
	s_branch .LBB0_26

; DI float bflo(unsigned u) { return __uint_as_float(u << 16); }
; DI float bfhi(unsigned u) { return __uint_as_float(u & 0xffff0000u); }
; DI void phase_normmod(ArgsP a, int tb_, int l, int which, bool first, bool addp, bool ctx0, bool copyh, int MR, int vcu, int G) {
;     ...
;         const int br = m < ML ? (m >> 12) : 8; const bool isb = !first && m < ML;
;         f32x4 v[4]; float s = 0.f; u32x4 raw[4];
; #pragma unroll
;         for (int j = 0; j < 4; ++j) raw[j] = nraw[j];
;         { const int mn = m + NGW; if (mn < MR) NM_LOAD(mn, nraw); }
;         const f32x4* gp = (const f32x4*)g + lane; const f32x4* sh = (const f32x4*)(mod + (size_t)br * (NMOD * D) + (3 * which) * D) + lane; const f32x4* scp = (const f32x4*)(mod + (size_t)br * (NMOD * D) + (3 * which + 1) * D) + lane;
;         f32x4 gv[4], sv[4], cv[4];
; #pragma unroll
;         for (int j = 0; j < 4; ++j) { gv[j] = gp[64 * j]; sv[j] = sh[64 * j]; cv[j] = scp[64 * j] + 1.f; }
; #pragma unroll
;         for (int j = 0; j < 4; ++j) { v[j] = isb ? (f32x4){bflo(raw[j].x), bfhi(raw[j].x), bflo(raw[j].y), bfhi(raw[j].y)} : __builtin_bit_cast(f32x4, raw[j]);
;             s += (v[j].x * v[j].x + v[j].y * v[j].y) + (v[j].z * v[j].z + v[j].w * v[j].w); }
;         if (copyh && isb) { u32x2* c = (u32x2*)(hcopy + (size_t)m * D) + lane;
; #pragma unroll
;             for (int j = 0; j < 4; ++j) c[64 * j] = (u32x2){raw[j].x, raw[j].y}; }
;         if (addp && m >= ML) { const f32x4* pp = (const f32x4*)((const float*)(a->ws + A_PART) + (size_t)(m - ML) * D) + lane; s = 0.f;
; #pragma unroll
;             for (int jh = 0; jh < 2; ++jh) { f32x4 pv[2][8];
; #pragma unroll
;                 for (int jj = 0; jj < 2; ++jj)
; #pragma unroll
;                     for (int p = 0; p < 8; ++p) pv[jj][p] = pp[(size_t)p * MC * (D / 4) + 64 * (2 * jh + jj)];
;                 __builtin_amdgcn_sched_barrier(0);
; #pragma unroll
;                 for (int jj = 0; jj < 2; ++jj) { const int j = 2 * jh + jj;
; #pragma unroll
;                     for (int p = 0; p < 8; ++p) v[j] = v[j] + pv[jj][p];
;                     s += (v[j].x * v[j].x + v[j].y * v[j].y) + (v[j].z * v[j].z + v[j].w * v[j].w); } }
;             float* hrow = hc + (size_t)(m - ML) * D;
; #pragma unroll
;             for (int j = 0; j < 4; ++j) ((f32x4*)hrow + lane)[64 * j] = v[j]; }
.LBB0_26:
	s_or_b64 exec, exec, s[18:19]
	v_lshlrev_b32_e32 v93, 16, v68
	v_and_b32_e32 v96, 0xffff0000, v68
	v_lshlrev_b32_e32 v97, 16, v69
	v_and_b32_e32 v98, 0xffff0000, v69
	v_cmp_gt_i32_e32 vcc, s74, v95
	s_movk_i32 s0, 0x7fff
	s_nop 0
	v_cndmask_b32_e32 v71, v71, v98, vcc
	v_cndmask_b32_e32 v70, v70, v97, vcc
	v_cndmask_b32_e32 v69, v69, v96, vcc
	v_cndmask_b32_e32 v68, v68, v93, vcc
	v_pk_mul_f32 v[96:97], v[70:71], v[70:71]
	v_pk_mul_f32 v[98:99], v[68:69], v[68:69]
	v_lshlrev_b32_e32 v93, 16, v64
	v_pk_mov_b32 v[100:101], v[98:99], v[96:97] op_sel:[1,0]
	v_mov_b32_e32 v99, v97
	v_pk_add_f32 v[96:97], v[100:101], v[98:99]
	v_and_b32_e32 v98, 0xffff0000, v64
	v_lshlrev_b32_e32 v99, 16, v65
	v_and_b32_e32 v100, 0xffff0000, v65
	v_cndmask_b32_e32 v67, v67, v100, vcc
	v_cndmask_b32_e32 v66, v66, v99, vcc
	v_cndmask_b32_e32 v65, v65, v98, vcc
	v_cndmask_b32_e32 v64, v64, v93, vcc
	v_pk_mul_f32 v[98:99], v[66:67], v[66:67]
	v_pk_mul_f32 v[100:101], v[64:65], v[64:65]
	v_lshlrev_b32_e32 v93, 16, v76
	v_pk_mov_b32 v[102:103], v[100:101], v[98:99] op_sel:[1,0]
	v_mov_b32_e32 v101, v99
	v_pk_add_f32 v[98:99], v[102:103], v[100:101]
	v_and_b32_e32 v100, 0xffff0000, v76
	v_lshlrev_b32_e32 v101, 16, v77
	v_and_b32_e32 v102, 0xffff0000, v77
	v_cndmask_b32_e32 v77, v77, v100, vcc
	v_cndmask_b32_e32 v76, v76, v93, vcc
	v_lshlrev_b32_e32 v93, 16, v48
	v_and_b32_e32 v100, 0xffff0000, v48
	v_cndmask_b32_e32 v79, v79, v102, vcc
	v_cndmask_b32_e32 v78, v78, v101, vcc
	v_lshlrev_b32_e32 v101, 16, v49
	v_and_b32_e32 v102, 0xffff0000, v49
	v_cndmask_b32_e32 v49, v49, v100, vcc
	v_cndmask_b32_e32 v48, v48, v93, vcc
	v_mul_f32_e32 v93, v48, v48
	v_mul_f32_e32 v100, v49, v49
	v_pk_add_f32 v[96:97], v[96:97], v[96:97] op_sel:[0,1] op_sel_hi:[1,0]
	v_pk_add_f32 v[98:99], v[98:99], v[98:99] op_sel:[0,1] op_sel_hi:[1,0]
	v_mov_b32_e32 v97, v93
	v_mov_b32_e32 v99, v100
	v_cndmask_b32_e32 v50, v50, v101, vcc
	v_pk_add_f32 v[96:97], v[96:97], v[98:99]
	v_mul_f32_e32 v98, v77, v77
	v_cndmask_b32_e32 v51, v51, v102, vcc
	v_mul_f32_e32 v101, v50, v50
	v_pk_fma_f32 v[98:99], v[76:77], v[76:77], v[98:99] op_sel_hi:[1,1,0]
	v_mul_f32_e32 v100, v79, v79
	v_mul_f32_e32 v102, v51, v51
	v_mov_b32_e32 v99, v101
	v_pk_fma_f32 v[100:101], v[78:79], v[78:79], v[100:101] op_sel_hi:[1,1,0]
	v_cmp_lt_i32_e32 vcc, s0, v95
	v_mov_b32_e32 v101, v102
	v_pk_add_f32 v[98:99], v[98:99], v[100:101]
	s_nop 0
	v_pk_add_f32 v[96:97], v[96:97], v[98:99]
	s_nop 0
	v_add_f32_e32 v93, v96, v97
	s_and_saveexec_b64 s[18:19], vcc
	s_cbranch_execz .LBB0_19
	v_mov_b32_e32 v95, v189
	v_lshlrev_b64 v[94:95], 12, v[94:95]
	v_lshl_add_u64 v[102:103], v[82:83], 0, v[94:95]
	v_add_co_u32_e32 v100, vcc, 0x800000, v102
	s_nop 1
	v_addc_co_u32_e32 v101, vcc, 0, v103, vcc
	v_add_co_u32_e32 v104, vcc, 0x1000000, v102
	s_nop 1
	v_addc_co_u32_e32 v105, vcc, 0, v103, vcc
	v_add_co_u32_e32 v106, vcc, 0x1800000, v102
	s_nop 1
	v_addc_co_u32_e32 v107, vcc, 0, v103, vcc
	v_add_co_u32_e32 v108, vcc, 0x2000000, v102
	s_nop 1
	v_addc_co_u32_e32 v109, vcc, 0, v103, vcc
	v_add_co_u32_e32 v110, vcc, 0x2800000, v102
	s_nop 1
	v_addc_co_u32_e32 v111, vcc, 0, v103, vcc
	v_add_co_u32_e32 v112, vcc, 0x3000000, v102
	s_nop 1
	v_addc_co_u32_e32 v113, vcc, 0, v103, vcc
	v_add_co_u32_e32 v114, vcc, 0x3800000, v102
	s_nop 1
	v_addc_co_u32_e32 v115, vcc, 0, v103, vcc
	global_load_dwordx4 v[96:99], v[102:103], off
	global_load_dwordx4 v[122:125], v[102:103], off offset:1024
	global_load_dwordx4 v[126:129], v[100:101], off
	global_load_dwordx4 v[130:133], v[100:101], off offset:1024
	global_load_dwordx4 v[134:137], v[104:105], off
	global_load_dwordx4 v[138:141], v[104:105], off offset:1024
	global_load_dwordx4 v[142:145], v[106:107], off
	global_load_dwordx4 v[146:149], v[106:107], off offset:1024
	global_load_dwordx4 v[150:153], v[108:109], off
	global_load_dwordx4 v[154:157], v[108:109], off offset:1024
	global_load_dwordx4 v[158:161], v[110:111], off
	global_load_dwordx4 v[162:165], v[110:111], off offset:1024
	global_load_dwordx4 v[166:169], v[112:113], off
	global_load_dwordx4 v[170:173], v[112:113], off offset:1024
	global_load_dwordx4 v[174:177], v[114:115], off
	global_load_dwordx4 v[178:181], v[114:115], off offset:1024
	s_waitcnt vmcnt(15)
	v_pk_add_f32 v[70:71], v[98:99], v[70:71]
	v_pk_add_f32 v[68:69], v[96:97], v[68:69]
	s_waitcnt vmcnt(13)
	v_pk_add_f32 v[70:71], v[70:71], v[128:129]
	v_pk_add_f32 v[68:69], v[68:69], v[126:127]
	s_waitcnt vmcnt(11)
	v_pk_add_f32 v[70:71], v[70:71], v[136:137]
	v_pk_add_f32 v[68:69], v[68:69], v[134:135]
	v_pk_add_f32 v[66:67], v[124:125], v[66:67]
	v_pk_add_f32 v[64:65], v[122:123], v[64:65]
	s_waitcnt vmcnt(9)
	v_pk_add_f32 v[70:71], v[70:71], v[144:145]
	v_pk_add_f32 v[68:69], v[68:69], v[142:143]
	v_pk_add_f32 v[66:67], v[66:67], v[132:133]
	v_pk_add_f32 v[64:65], v[64:65], v[130:131]
	s_waitcnt vmcnt(7)
	v_pk_add_f32 v[70:71], v[70:71], v[152:153]
	v_pk_add_f32 v[68:69], v[68:69], v[150:151]
	v_pk_add_f32 v[66:67], v[66:67], v[140:141]
	v_pk_add_f32 v[64:65], v[64:65], v[138:139]
	s_waitcnt vmcnt(5)
; DI unsigned cvtpk(float lo, float hi) { f32x2_t v = {lo, hi}; bf16x2_t b = __builtin_convertvector(v, bf16x2_t); return __builtin_bit_cast(unsigned, b); }
; DI void phase_normmod(ArgsP a, int tb_, int l, int which, bool first, bool addp, bool ctx0, bool copyh, int MR, int vcu, int G) {
;     ...
;         if (addp && m >= ML) { const f32x4* pp = (const f32x4*)((const float*)(a->ws + A_PART) + (size_t)(m - ML) * D) + lane; s = 0.f;
; #pragma unroll
;             for (int jh = 0; jh < 2; ++jh) { f32x4 pv[2][8];
; #pragma unroll
;                 for (int jj = 0; jj < 2; ++jj)
; #pragma unroll
;                     for (int p = 0; p < 8; ++p) pv[jj][p] = pp[(size_t)p * MC * (D / 4) + 64 * (2 * jh + jj)];
;                 __builtin_amdgcn_sched_barrier(0);
; #pragma unroll
;                 for (int jj = 0; jj < 2; ++jj) { const int j = 2 * jh + jj;
; #pragma unroll
;                     for (int p = 0; p < 8; ++p) v[j] = v[j] + pv[jj][p];
;                     s += (v[j].x * v[j].x + v[j].y * v[j].y) + (v[j].z * v[j].z + v[j].w * v[j].w); } }
;             float* hrow = hc + (size_t)(m - ML) * D;
; #pragma unroll
;             for (int j = 0; j < 4; ++j) ((f32x4*)hrow + lane)[64 * j] = v[j]; }
;         const float r = rsqrtf(wave_sum(s, lane) * (1.f / D) + EPS);
;         u32x2* o = (u32x2*)(U + (size_t)m * D) + lane;
; #pragma unroll
;         for (int j = 0; j < 4; ++j) { const f32x4 y = v[j] * r * gv[j]; const f32x4 u = y * cv[j] + sv[j]; u32x2 w; w.x = cvtpk(u.x, u.y); w.y = cvtpk(u.z, u.w); o[64 * j] = w; }
;     }
	v_pk_add_f32 v[70:71], v[70:71], v[160:161]
	v_pk_add_f32 v[68:69], v[68:69], v[158:159]
	v_pk_add_f32 v[66:67], v[66:67], v[148:149]
	v_pk_add_f32 v[64:65], v[64:65], v[146:147]
	s_waitcnt vmcnt(3)
	v_pk_add_f32 v[70:71], v[70:71], v[168:169]
	v_pk_add_f32 v[68:69], v[68:69], v[166:167]
	v_pk_add_f32 v[66:67], v[66:67], v[156:157]
	v_pk_add_f32 v[64:65], v[64:65], v[154:155]
	s_waitcnt vmcnt(1)
	v_pk_add_f32 v[70:71], v[70:71], v[176:177]
	v_pk_add_f32 v[68:69], v[68:69], v[174:175]
	v_pk_add_f32 v[66:67], v[66:67], v[164:165]
	v_pk_add_f32 v[64:65], v[64:65], v[162:163]
	v_pk_mul_f32 v[96:97], v[70:71], v[70:71]
	v_pk_mul_f32 v[98:99], v[68:69], v[68:69]
	v_pk_add_f32 v[66:67], v[66:67], v[172:173]
	v_pk_add_f32 v[64:65], v[64:65], v[170:171]
	v_pk_mov_b32 v[126:127], v[98:99], v[96:97] op_sel:[1,0]
	v_mov_b32_e32 v99, v97
	s_waitcnt vmcnt(0)
	v_pk_add_f32 v[66:67], v[66:67], v[180:181]
	v_pk_add_f32 v[64:65], v[64:65], v[178:179]
	v_pk_add_f32 v[96:97], v[126:127], v[98:99]
	v_pk_mul_f32 v[98:99], v[66:67], v[66:67]
	v_pk_mul_f32 v[122:123], v[64:65], v[64:65]
	s_nop 0
	v_pk_mov_b32 v[124:125], v[122:123], v[98:99] op_sel:[1,0]
	v_mov_b32_e32 v123, v99
	v_pk_add_f32 v[98:99], v[124:125], v[122:123]
	global_load_dwordx4 v[122:125], v[102:103], off offset:2048
	global_load_dwordx4 v[126:129], v[100:101], off offset:2048
	global_load_dwordx4 v[130:133], v[104:105], off offset:2048
	global_load_dwordx4 v[134:137], v[106:107], off offset:2048
	global_load_dwordx4 v[138:141], v[108:109], off offset:2048
	global_load_dwordx4 v[142:145], v[110:111], off offset:2048
	global_load_dwordx4 v[146:149], v[112:113], off offset:2048
	global_load_dwordx4 v[150:153], v[114:115], off offset:2048
	global_load_dwordx4 v[154:157], v[102:103], off offset:3072
	s_nop 0
	global_load_dwordx4 v[100:103], v[100:101], off offset:3072
	s_nop 0
	global_load_dwordx4 v[158:161], v[104:105], off offset:3072
	s_nop 0
	global_load_dwordx4 v[104:107], v[106:107], off offset:3072
	s_nop 0
	global_load_dwordx4 v[162:165], v[108:109], off offset:3072
	s_nop 0
	global_load_dwordx4 v[108:111], v[110:111], off offset:3072
	s_nop 0
	global_load_dwordx4 v[166:169], v[112:113], off offset:3072
	s_nop 0
	global_load_dwordx4 v[112:115], v[114:115], off offset:3072
	s_waitcnt vmcnt(7)
	v_pk_add_f32 v[48:49], v[154:155], v[48:49]
	v_pk_add_f32 v[76:77], v[122:123], v[76:77]
	s_waitcnt vmcnt(6)
	v_pk_add_f32 v[48:49], v[48:49], v[100:101]
	v_pk_add_f32 v[78:79], v[124:125], v[78:79]
	s_waitcnt vmcnt(5)
	v_pk_add_f32 v[48:49], v[48:49], v[158:159]
	v_pk_add_f32 v[76:77], v[76:77], v[126:127]
	v_pk_add_f32 v[50:51], v[156:157], v[50:51]
	s_waitcnt vmcnt(4)
	v_pk_add_f32 v[48:49], v[48:49], v[104:105]
	v_pk_add_f32 v[78:79], v[78:79], v[128:129]
	v_pk_add_f32 v[76:77], v[76:77], v[130:131]
	v_pk_add_f32 v[50:51], v[50:51], v[102:103]
	s_waitcnt vmcnt(3)
	v_pk_add_f32 v[48:49], v[48:49], v[162:163]
	v_pk_add_f32 v[78:79], v[78:79], v[132:133]
	v_pk_add_f32 v[76:77], v[76:77], v[134:135]
	v_pk_add_f32 v[50:51], v[50:51], v[160:161]
	s_waitcnt vmcnt(2)
	v_pk_add_f32 v[48:49], v[48:49], v[108:109]
	v_pk_add_f32 v[78:79], v[78:79], v[136:137]
	v_pk_add_f32 v[76:77], v[76:77], v[138:139]
	v_pk_add_f32 v[50:51], v[50:51], v[106:107]
	s_waitcnt vmcnt(1)
	v_pk_add_f32 v[48:49], v[48:49], v[166:167]
	v_pk_add_f32 v[78:79], v[78:79], v[140:141]
	v_pk_add_f32 v[76:77], v[76:77], v[142:143]
	v_pk_add_f32 v[50:51], v[50:51], v[164:165]
	s_waitcnt vmcnt(0)
	v_pk_add_f32 v[48:49], v[48:49], v[112:113]
	v_pk_add_f32 v[78:79], v[78:79], v[144:145]
	v_pk_add_f32 v[76:77], v[76:77], v[146:147]
	v_pk_add_f32 v[50:51], v[50:51], v[110:111]
	v_mul_f32_e32 v93, v48, v48
	v_mul_f32_e32 v100, v49, v49
	v_pk_add_f32 v[96:97], v[96:97], v[96:97] op_sel:[0,1] op_sel_hi:[1,0]
	v_pk_add_f32 v[98:99], v[98:99], v[98:99] op_sel:[0,1] op_sel_hi:[1,0]
	v_pk_add_f32 v[78:79], v[78:79], v[148:149]
	v_pk_add_f32 v[76:77], v[76:77], v[150:151]
	v_pk_add_f32 v[50:51], v[50:51], v[168:169]
	v_mov_b32_e32 v97, v93
	v_mov_b32_e32 v99, v100
	v_pk_add_f32 v[78:79], v[78:79], v[152:153]
	v_pk_add_f32 v[50:51], v[50:51], v[114:115]
	v_pk_add_f32 v[96:97], v[96:97], v[98:99]
	v_mul_f32_e32 v98, v77, v77
	v_mul_f32_e32 v101, v50, v50
	v_pk_fma_f32 v[98:99], v[76:77], v[76:77], v[98:99] op_sel_hi:[1,1,0]
	v_mul_f32_e32 v100, v79, v79
	v_mul_f32_e32 v102, v51, v51
	v_mov_b32_e32 v99, v101
	v_pk_fma_f32 v[100:101], v[78:79], v[78:79], v[100:101] op_sel_hi:[1,1,0]
	v_lshl_add_u64 v[94:95], v[84:85], 0, v[94:95]
	v_mov_b32_e32 v101, v102
	v_pk_add_f32 v[98:99], v[98:99], v[100:101]
	global_store_dwordx4 v[94:95], v[68:71], off
	global_store_dwordx4 v[94:95], v[64:67], off offset:1024
	global_store_dwordx4 v[94:95], v[76:79], off offset:2048
	global_store_dwordx4 v[94:95], v[48:51], off offset:3072
	v_pk_add_f32 v[96:97], v[96:97], v[98:99]
	s_nop 0
	v_add_f32_e32 v93, v96, v97
	s_branch .LBB0_19

; DI void phase_normmod(ArgsP a, int tb_, int l, int which, bool first, bool addp, bool ctx0, bool copyh, int MR, int vcu, int G) {
;     int tid_ = tb_ + lane_asm(); asm volatile("" : "+v"(tid_)); const int tid = tid_, lane = tid & 63, wave = tid >> 6;
;     const int gw = vcu * NWAVES + wave, NGW = G * NWAVES;
;     const float* g = (which == 0 ? a->in[I_GFFN1] : which == 1 ? a->in[I_GMIX] : a->in[I_GFFN2]) + l * D;
;     const float* mod = (const float*)(a->ws + WS_MOD) + (size_t)l * 9 * (NMOD * D);
;     float* hc = (float*)(a->ws + WS_HC); bf16_t* U = (bf16_t*)(a->ws + WS_U); const bf16_t* hb16 = (const bf16_t*)a->out; bf16_t* hcopy = (bf16_t*)(a->ws + A_HCOPY);
;     ...
;     u32x4 nraw[4];
;     if (gw < MR) NM_LOAD(gw, nraw);
;     for (int m = gw; m < MR; m += NGW) {
;         const int br = m < ML ? (m >> 12) : 8; const bool isb = !first && m < ML;
;         f32x4 v[4]; float s = 0.f; u32x4 raw[4];
; #pragma unroll
;         for (int j = 0; j < 4; ++j) raw[j] = nraw[j];
;         { const int mn = m + NGW; if (mn < MR) NM_LOAD(mn, nraw); }
;         const f32x4* gp = (const f32x4*)g + lane; const f32x4* sh = (const f32x4*)(mod + (size_t)br * (NMOD * D) + (3 * which) * D) + lane; const f32x4* scp = (const f32x4*)(mod + (size_t)br * (NMOD * D) + (3 * which + 1) * D) + lane;
;         f32x4 gv[4], sv[4], cv[4];
; #pragma unroll
;         for (int j = 0; j < 4; ++j) { gv[j] = gp[64 * j]; sv[j] = sh[64 * j]; cv[j] = scp[64 * j] + 1.f; }
; #pragma unroll
;         for (int j = 0; j < 4; ++j) { v[j] = isb ? (f32x4){bflo(raw[j].x), bfhi(raw[j].x), bflo(raw[j].y), bfhi(raw[j].y)} : __builtin_bit_cast(f32x4, raw[j]);
;             s += (v[j].x * v[j].x + v[j].y * v[j].y) + (v[j].z * v[j].z + v[j].w * v[j].w); }
;         if (copyh && isb) { u32x2* c = (u32x2*)(hcopy + (size_t)m * D) + lane;
; #pragma unroll
;             for (int j = 0; j < 4; ++j) c[64 * j] = (u32x2){raw[j].x, raw[j].y}; }
;         if (addp && m >= ML) { const f32x4* pp = (const f32x4*)((const float*)(a->ws + A_PART) + (size_t)(m - ML) * D) + lane; s = 0.f;
; #pragma unroll
;             for (int jh = 0; jh < 2; ++jh) { f32x4 pv[2][8];
; #pragma unroll
;                 for (int jj = 0; jj < 2; ++jj)
; #pragma unroll
;                     for (int p = 0; p < 8; ++p) pv[jj][p] = pp[(size_t)p * MC * (D / 4) + 64 * (2 * jh + jj)];
;                 __builtin_amdgcn_sched_barrier(0);
; #pragma unroll
.LBB0_730:
	s_or_b64 exec, exec, s[18:19]
	v_readlane_b32 s4, v255, 31
	v_readlane_b32 s5, v255, 32
	s_lshl_b32 s18, s2, 3
	s_lshl_b64 s[4:5], s[4:5], 2
	s_waitcnt lgkmcnt(0)
	s_add_u32 s4, s20, s4
	s_addc_u32 s5, s21, s5
	v_readlane_b32 s20, v255, 33
	v_readlane_b32 s21, v255, 34
	s_lshl_b64 s[20:21], s[20:21], 2
	s_add_u32 s2, s10, s20
	s_addc_u32 s7, s11, s21
	s_add_u32 s20, s2, 0x103000
	v_lshlrev_b32_e32 v1, 2, v80
	s_addc_u32 s21, s7, 0
	v_xor_b32_e32 v116, 4, v1
	v_xor_b32_e32 v117, 8, v1
	v_xor_b32_e32 v118, 16, v1
	v_xor_b32_e32 v119, 32, v1
	v_xor_b32_e32 v120, 64, v1
	v_xor_b32_e32 v121, 0x80, v1
	v_ashrrev_i32_e32 v1, 31, v0
	s_ashr_i32 s7, s6, 31
	s_add_i32 s2, s6, s18
	v_lshlrev_b64 v[4:5], 4, v[80:81]
	v_add_u32_e32 v94, 0xffff8000, v2
	v_lshl_add_u64 v[2:3], v[0:1], 0, s[6:7]
	v_add_u32_e32 v0, s2, v0
	v_lshl_add_u64 v[82:83], s[4:5], 0, v[4:5]
	v_lshl_add_u64 v[6:7], s[10:11], 0, v[4:5]
	s_mov_b64 s[4:5], 0x14a00000
	v_lshlrev_b64 v[2:3], 11, v[2:3]
	v_ashrrev_i32_e32 v1, 31, v0
	v_lshl_add_u64 v[84:85], v[6:7], 0, s[4:5]
	v_lshl_add_u64 v[2:3], s[10:11], 0, v[2:3]
	s_mov_b64 s[4:5], 0xa00400
	s_ashr_i32 s19, s18, 31
	v_lshlrev_b64 v[0:1], 11, v[0:1]
	v_lshl_add_u64 v[86:87], s[16:17], 0, v[4:5]
	v_lshl_add_u64 v[88:89], v[2:3], 0, s[4:5]
	v_lshlrev_b64 v[90:91], 3, v[80:81]
	s_lshl_b64 s[10:11], s[18:19], 11
	v_lshl_add_u64 v[92:93], s[8:9], 0, v[0:1]
	s_mov_b64 s[8:9], 0
	s_waitcnt vmcnt(0)
	s_branch .LBB0_732
.LBB0_731:
	s_or_b64 exec, exec, s[22:23]
	s_waitcnt vmcnt(5)
	v_pk_add_f32 v[74:75], v[74:75], 1.0 op_sel_hi:[1,0]
	v_pk_add_f32 v[72:73], v[72:73], 1.0 op_sel_hi:[1,0]
	v_pk_add_f32 v[62:63], v[62:63], 1.0 op_sel_hi:[1,0]
	v_pk_add_f32 v[60:61], v[60:61], 1.0 op_sel_hi:[1,0]
	v_pk_add_f32 v[58:59], v[58:59], 1.0 op_sel_hi:[1,0]
	v_pk_add_f32 v[56:57], v[56:57], 1.0 op_sel_hi:[1,0]
	s_waitcnt vmcnt(4)
	v_pk_add_f32 v[54:55], v[54:55], 1.0 op_sel_hi:[1,0]
	v_pk_add_f32 v[52:53], v[52:53], 1.0 op_sel_hi:[1,0]
	s_and_b64 s[4:5], exec, s[6:7]
	s_or_b64 s[8:9], s[4:5], s[8:9]
	v_add_f32_dpp v94, v95, v95 quad_perm:[1,0,3,2] row_mask:0xf bank_mask:0xf
	s_nop 1
	v_add_f32_dpp v94, v94, v94 quad_perm:[2,3,0,1] row_mask:0xf bank_mask:0xf
	s_nop 1
	v_add_f32_dpp v94, v94, v94 row_half_mirror row_mask:0xf bank_mask:0xf
	s_nop 1
	v_add_f32_dpp v94, v94, v94 row_mirror row_mask:0xf bank_mask:0xf
	s_nop 1
	v_add_f32_dpp v94, v94, v94 row_bcast:15 row_mask:0xa bank_mask:0xf
	s_nop 1
	v_add_f32_dpp v94, v94, v94 row_bcast:31 row_mask:0xc bank_mask:0xf
	s_nop 0
	v_readlane_b32 vcc_lo, v94, 63
	s_nop 1
	v_mov_b32_e32 v94, vcc_lo
	v_fmamk_f32 v94, v94, 0x3a800000, v230
	v_mul_f32_e32 v95, 0x4b800000, v94
	v_cmp_gt_f32_e32 vcc, s76, v94
	s_nop 1
	v_cndmask_b32_e32 v94, v94, v95, vcc
	v_rsq_f32_e32 v96, v94
	v_lshl_add_u64 v[94:95], v[88:89], 0, v[90:91]
	v_lshl_add_u64 v[90:91], v[90:91], 0, s[10:11]
	v_mul_f32_e32 v97, 0x45800000, v96
	v_cndmask_b32_e32 v96, v96, v97, vcc
	v_pk_mul_f32 v[70:71], v[70:71], v[96:97] op_sel_hi:[1,0]
	v_pk_mul_f32 v[68:69], v[68:69], v[96:97] op_sel_hi:[1,0]
	v_pk_mul_f32 v[78:79], v[78:79], v[96:97] op_sel_hi:[1,0]
	v_pk_mul_f32 v[76:77], v[76:77], v[96:97] op_sel_hi:[1,0]
	v_pk_mul_f32 v[66:67], v[66:67], v[96:97] op_sel_hi:[1,0]
	v_pk_mul_f32 v[64:65], v[64:65], v[96:97] op_sel_hi:[1,0]
	v_pk_mul_f32 v[32:33], v[32:33], v[68:69]
	v_pk_mul_f32 v[34:35], v[34:35], v[70:71]
	v_pk_mul_f32 v[28:29], v[28:29], v[76:77]
	v_pk_mul_f32 v[30:31], v[30:31], v[78:79]
	v_pk_mul_f32 v[44:45], v[44:45], v[64:65]
	v_pk_mul_f32 v[46:47], v[46:47], v[66:67]
	v_pk_fma_f32 v[34:35], v[74:75], v[34:35], v[42:43]
	v_pk_fma_f32 v[32:33], v[72:73], v[32:33], v[40:41]
	v_pk_fma_f32 v[26:27], v[62:63], v[30:31], v[26:27]
	v_pk_fma_f32 v[24:25], v[60:61], v[28:29], v[24:25]
	v_pk_fma_f32 v[38:39], v[58:59], v[46:47], v[38:39]
	v_pk_fma_f32 v[36:37], v[56:57], v[44:45], v[36:37]
	v_cvt_pk_bf16_f32 v32, v32, v33
	v_cvt_pk_bf16_f32 v33, v34, v35
	v_cvt_pk_bf16_f32 v24, v24, v25
	v_cvt_pk_bf16_f32 v25, v26, v27
	v_cvt_pk_bf16_f32 v34, v36, v37
	v_cvt_pk_bf16_f32 v35, v38, v39
	global_store_dwordx2 v[94:95], v[32:33], off offset:-1024
	global_store_dwordx2 v[94:95], v[34:35], off offset:-512
	global_store_dwordx2 v[94:95], v[24:25], off
	v_pk_mul_f32 v[24:25], v[50:51], v[96:97] op_sel_hi:[1,0]
	v_pk_mul_f32 v[26:27], v[48:49], v[96:97] op_sel_hi:[1,0]
	v_pk_mul_f32 v[22:23], v[22:23], v[24:25]
	v_pk_mul_f32 v[20:21], v[20:21], v[26:27]
	v_pk_fma_f32 v[18:19], v[54:55], v[22:23], v[18:19]
	v_pk_fma_f32 v[16:17], v[52:53], v[20:21], v[16:17]
	s_waitcnt vmcnt(3)
	v_mov_b32_e32 v68, v0
	v_cvt_pk_bf16_f32 v16, v16, v17
	v_cvt_pk_bf16_f32 v17, v18, v19
	global_store_dwordx2 v[94:95], v[16:17], off offset:512
	v_mov_b32_e32 v94, v188
	v_mov_b32_e32 v69, v1
	v_mov_b32_e32 v70, v2
	v_mov_b32_e32 v71, v3
	v_mov_b32_e32 v64, v4
	v_mov_b32_e32 v65, v5
	v_mov_b32_e32 v66, v6
	v_mov_b32_e32 v67, v7
	v_mov_b32_e32 v76, v8
	v_mov_b32_e32 v77, v9
	v_mov_b32_e32 v78, v10
	v_mov_b32_e32 v79, v11
	v_mov_b32_e32 v48, v12
	v_mov_b32_e32 v49, v13
	v_mov_b32_e32 v50, v14
	v_mov_b32_e32 v51, v15
	s_andn2_b64 exec, exec, s[8:9]
	s_cbranch_execz .LBB0_742
; DI void phase_normmod(ArgsP a, int tb_, int l, int which, bool first, bool addp, bool ctx0, bool copyh, int MR, int vcu, int G) {
;     ...
;     for (int m = gw; m < MR; m += NGW) {
;         const int br = m < ML ? (m >> 12) : 8; const bool isb = !first && m < ML;
;         f32x4 v[4]; float s = 0.f; u32x4 raw[4];
; #pragma unroll
;         for (int j = 0; j < 4; ++j) raw[j] = nraw[j];
;         { const int mn = m + NGW; if (mn < MR) NM_LOAD(mn, nraw); }
;         const f32x4* gp = (const f32x4*)g + lane; const f32x4* sh = (const f32x4*)(mod + (size_t)br * (NMOD * D) + (3 * which) * D) + lane; const f32x4* scp = (const f32x4*)(mod + (size_t)br * (NMOD * D) + (3 * which + 1) * D) + lane;
;         f32x4 gv[4], sv[4], cv[4];
; #pragma unroll
;         for (int j = 0; j < 4; ++j) { gv[j] = gp[64 * j]; sv[j] = sh[64 * j]; cv[j] = scp[64 * j] + 1.f; }
.LBB0_732:
	v_add_u32_e32 v104, 0x8000, v94
	v_min_i32_e32 v16, 0x8000, v104
	v_ashrrev_i32_e32 v16, 12, v16
	v_mul_hi_i32_i24_e32 v17, 0x9000, v16
	v_mul_i32_i24_e32 v16, 0x9000, v16
	v_lshl_add_u64 v[16:17], s[20:21], 0, v[16:17]
	v_lshl_add_u64 v[16:17], v[80:81], 4, v[16:17]
	s_mov_b64 s[4:5], 0x1000
	v_add_co_u32_e32 v54, vcc, s93, v16
	v_lshl_add_u64 v[52:53], v[16:17], 0, s[4:5]
	s_nop 0
	v_addc_co_u32_e32 v55, vcc, 0, v17, vcc
	global_load_dwordx4 v[32:35], v[82:83], off
	global_load_dwordx4 v[44:47], v[82:83], off offset:1024
	global_load_dwordx4 v[40:43], v[16:17], off
	global_load_dwordx4 v[36:39], v[16:17], off offset:1024
	global_load_dwordx4 v[56:59], v[52:53], off offset:1024
	global_load_dwordx4 v[60:63], v[52:53], off offset:2048
	global_load_dwordx4 v[28:31], v[82:83], off offset:2048
	global_load_dwordx4 v[20:23], v[82:83], off offset:3072
	global_load_dwordx4 v[24:27], v[16:17], off offset:2048
	s_nop 0
	global_load_dwordx4 v[16:19], v[16:17], off offset:3072
	s_nop 0
	global_load_dwordx4 v[72:75], v[54:55], off
	s_nop 0
	global_load_dwordx4 v[52:55], v[52:53], off offset:3072
	v_add_u32_e32 v188, s18, v94
	v_add_u32_e32 v200, 0x8000, v188
	v_cmp_gt_i32_e32 vcc, s63, v200
	v_cmp_lt_i32_e64 s[6:7], s70, v200
	v_mov_b32_e32 v0, v68
	v_mov_b32_e32 v1, v69
	v_mov_b32_e32 v2, v70
	v_mov_b32_e32 v3, v71
	v_mov_b32_e32 v4, v64
	v_mov_b32_e32 v5, v65
	v_mov_b32_e32 v6, v66
	v_mov_b32_e32 v7, v67
	v_mov_b32_e32 v8, v76
	v_mov_b32_e32 v9, v77
	v_mov_b32_e32 v10, v78
	v_mov_b32_e32 v11, v79
	v_mov_b32_e32 v12, v48
	v_mov_b32_e32 v13, v49
	v_mov_b32_e32 v14, v50
	v_mov_b32_e32 v15, v51
	s_and_saveexec_b64 s[22:23], vcc
	s_cbranch_execz .Lnm_skip_732
	v_cmp_gt_i32_e32 vcc, s74, v200
	s_and_saveexec_b64 s[4:5], vcc
	s_xor_b64 s[24:25], exec, s[4:5]
	s_cbranch_execz .LBB0_735
	v_lshl_add_u64 v[2:3], v[92:93], 0, v[90:91]
	global_load_dwordx2 v[0:1], v[2:3], off
	global_load_dwordx2 v[4:5], v[2:3], off offset:512
	global_load_dwordx2 v[8:9], v[2:3], off offset:1024
	global_load_dwordx2 v[12:13], v[2:3], off offset:1536

.LBB0_739:
	s_or_b64 exec, exec, s[24:25]
	s_branch .LBB0_740

; DI float bflo(unsigned u) { return __uint_as_float(u << 16); }
; DI float bfhi(unsigned u) { return __uint_as_float(u & 0xffff0000u); }
; DI void phase_normmod(ArgsP a, int tb_, int l, int which, bool first, bool addp, bool ctx0, bool copyh, int MR, int vcu, int G) {
;     ...
; #pragma unroll
;         for (int j = 0; j < 4; ++j) { v[j] = isb ? (f32x4){bflo(raw[j].x), bfhi(raw[j].x), bflo(raw[j].y), bfhi(raw[j].y)} : __builtin_bit_cast(f32x4, raw[j]);
;             s += (v[j].x * v[j].x + v[j].y * v[j].y) + (v[j].z * v[j].z + v[j].w * v[j].w); }
;         if (copyh && isb) { u32x2* c = (u32x2*)(hcopy + (size_t)m * D) + lane;
; #pragma unroll
;             for (int j = 0; j < 4; ++j) c[64 * j] = (u32x2){raw[j].x, raw[j].y}; }
;         if (addp && m >= ML) { const f32x4* pp = (const f32x4*)((const float*)(a->ws + A_PART) + (size_t)(m - ML) * D) + lane; s = 0.f;
; #pragma unroll
;             for (int jh = 0; jh < 2; ++jh) { f32x4 pv[2][8];
; #pragma unroll
;                 for (int jj = 0; jj < 2; ++jj)
; #pragma unroll
;                     for (int p = 0; p < 8; ++p) pv[jj][p] = pp[(size_t)p * MC * (D / 4) + 64 * (2 * jh + jj)];
;                 __builtin_amdgcn_sched_barrier(0);
; #pragma unroll
;                 for (int jj = 0; jj < 2; ++jj) { const int j = 2 * jh + jj;
; #pragma unroll
;                     for (int p = 0; p < 8; ++p) v[j] = v[j] + pv[jj][p];
;                     s += (v[j].x * v[j].x + v[j].y * v[j].y) + (v[j].z * v[j].z + v[j].w * v[j].w); } }
;             float* hrow = hc + (size_t)(m - ML) * D;
; #pragma unroll
;             for (int j = 0; j < 4; ++j) ((f32x4*)hrow + lane)[64 * j] = v[j]; }
.LBB0_740:
	s_or_b64 exec, exec, s[22:23]
	v_lshlrev_b32_e32 v95, 16, v68
	v_and_b32_e32 v96, 0xffff0000, v68
	v_lshlrev_b32_e32 v97, 16, v69
	v_and_b32_e32 v98, 0xffff0000, v69
	v_cmp_gt_i32_e32 vcc, s74, v104
	s_movk_i32 s0, 0x7fff
	s_nop 0
	v_cndmask_b32_e32 v71, v71, v98, vcc
	v_cndmask_b32_e32 v70, v70, v97, vcc
	v_cndmask_b32_e32 v69, v69, v96, vcc
	v_cndmask_b32_e32 v68, v68, v95, vcc
	v_pk_mul_f32 v[96:97], v[70:71], v[70:71]
	v_pk_mul_f32 v[98:99], v[68:69], v[68:69]
	v_lshlrev_b32_e32 v95, 16, v64
	v_pk_mov_b32 v[100:101], v[98:99], v[96:97] op_sel:[1,0]
	v_mov_b32_e32 v99, v97
	v_pk_add_f32 v[96:97], v[100:101], v[98:99]
	v_and_b32_e32 v98, 0xffff0000, v64
	v_lshlrev_b32_e32 v99, 16, v65
	v_and_b32_e32 v100, 0xffff0000, v65
	v_cndmask_b32_e32 v67, v67, v100, vcc
	v_cndmask_b32_e32 v66, v66, v99, vcc
	v_cndmask_b32_e32 v65, v65, v98, vcc
	v_cndmask_b32_e32 v64, v64, v95, vcc
	v_pk_mul_f32 v[98:99], v[66:67], v[66:67]
	v_pk_mul_f32 v[100:101], v[64:65], v[64:65]
	v_lshlrev_b32_e32 v95, 16, v76
	v_pk_mov_b32 v[102:103], v[100:101], v[98:99] op_sel:[1,0]
	v_mov_b32_e32 v101, v99
	v_pk_add_f32 v[98:99], v[102:103], v[100:101]
	v_and_b32_e32 v100, 0xffff0000, v76
	v_lshlrev_b32_e32 v101, 16, v77
	v_and_b32_e32 v102, 0xffff0000, v77
	v_cndmask_b32_e32 v77, v77, v100, vcc
	v_cndmask_b32_e32 v76, v76, v95, vcc
	v_lshlrev_b32_e32 v95, 16, v48
	v_and_b32_e32 v100, 0xffff0000, v48
	v_cndmask_b32_e32 v79, v79, v102, vcc
	v_cndmask_b32_e32 v78, v78, v101, vcc
	v_lshlrev_b32_e32 v101, 16, v49
	v_and_b32_e32 v102, 0xffff0000, v49
	v_cndmask_b32_e32 v49, v49, v100, vcc
	v_cndmask_b32_e32 v48, v48, v95, vcc
	v_mul_f32_e32 v95, v48, v48
	v_mul_f32_e32 v100, v49, v49
	v_pk_add_f32 v[96:97], v[96:97], v[96:97] op_sel:[0,1] op_sel_hi:[1,0]
	v_pk_add_f32 v[98:99], v[98:99], v[98:99] op_sel:[0,1] op_sel_hi:[1,0]
	v_mov_b32_e32 v97, v95
	v_mov_b32_e32 v99, v100
	v_cndmask_b32_e32 v50, v50, v101, vcc
	v_pk_add_f32 v[96:97], v[96:97], v[98:99]
	v_mul_f32_e32 v98, v77, v77
	v_cndmask_b32_e32 v51, v51, v102, vcc
	v_mul_f32_e32 v101, v50, v50
	v_pk_fma_f32 v[98:99], v[76:77], v[76:77], v[98:99] op_sel_hi:[1,1,0]
	v_mul_f32_e32 v100, v79, v79
	v_mul_f32_e32 v102, v51, v51
	v_mov_b32_e32 v99, v101
	v_pk_fma_f32 v[100:101], v[78:79], v[78:79], v[100:101] op_sel_hi:[1,1,0]
	v_cmp_lt_i32_e32 vcc, s0, v104
	v_mov_b32_e32 v101, v102
	v_pk_add_f32 v[98:99], v[98:99], v[100:101]
	s_nop 0
	v_pk_add_f32 v[96:97], v[96:97], v[98:99]
	s_nop 0
	v_add_f32_e32 v95, v96, v97
	s_and_saveexec_b64 s[22:23], vcc
	s_cbranch_execz .LBB0_731
	v_mov_b32_e32 v95, v189
	v_lshlrev_b64 v[94:95], 12, v[94:95]
	v_lshl_add_u64 v[102:103], v[84:85], 0, v[94:95]
	v_add_co_u32_e32 v100, vcc, 0x800000, v102
	s_nop 1
	v_addc_co_u32_e32 v101, vcc, 0, v103, vcc
	v_add_co_u32_e32 v104, vcc, 0x1000000, v102
	s_nop 1
	v_addc_co_u32_e32 v105, vcc, 0, v103, vcc
	v_add_co_u32_e32 v106, vcc, 0x1800000, v102
	s_nop 1
	v_addc_co_u32_e32 v107, vcc, 0, v103, vcc
	v_add_co_u32_e32 v108, vcc, 0x2000000, v102
	s_nop 1
	v_addc_co_u32_e32 v109, vcc, 0, v103, vcc
	v_add_co_u32_e32 v110, vcc, 0x2800000, v102
	s_nop 1
	v_addc_co_u32_e32 v111, vcc, 0, v103, vcc
	v_add_co_u32_e32 v112, vcc, 0x3000000, v102
	s_nop 1
	v_addc_co_u32_e32 v113, vcc, 0, v103, vcc
	v_add_co_u32_e32 v114, vcc, 0x3800000, v102
	s_nop 1
	v_addc_co_u32_e32 v115, vcc, 0, v103, vcc
	global_load_dwordx4 v[96:99], v[102:103], off
	global_load_dwordx4 v[122:125], v[102:103], off offset:1024
	global_load_dwordx4 v[126:129], v[100:101], off
	global_load_dwordx4 v[130:133], v[100:101], off offset:1024
	global_load_dwordx4 v[134:137], v[104:105], off
	global_load_dwordx4 v[138:141], v[104:105], off offset:1024
	global_load_dwordx4 v[142:145], v[106:107], off
	global_load_dwordx4 v[146:149], v[106:107], off offset:1024
	global_load_dwordx4 v[150:153], v[108:109], off
	global_load_dwordx4 v[154:157], v[108:109], off offset:1024
	global_load_dwordx4 v[158:161], v[110:111], off
	global_load_dwordx4 v[162:165], v[110:111], off offset:1024
	global_load_dwordx4 v[166:169], v[112:113], off
	global_load_dwordx4 v[170:173], v[112:113], off offset:1024
	global_load_dwordx4 v[174:177], v[114:115], off
	global_load_dwordx4 v[178:181], v[114:115], off offset:1024
	s_waitcnt vmcnt(15)
	v_pk_add_f32 v[70:71], v[98:99], v[70:71]
	v_pk_add_f32 v[68:69], v[96:97], v[68:69]
	s_waitcnt vmcnt(13)
	v_pk_add_f32 v[70:71], v[70:71], v[128:129]
	v_pk_add_f32 v[68:69], v[68:69], v[126:127]
	s_waitcnt vmcnt(11)
	v_pk_add_f32 v[70:71], v[70:71], v[136:137]
	v_pk_add_f32 v[68:69], v[68:69], v[134:135]
	v_pk_add_f32 v[66:67], v[124:125], v[66:67]
	v_pk_add_f32 v[64:65], v[122:123], v[64:65]
	s_waitcnt vmcnt(9)
	v_pk_add_f32 v[70:71], v[70:71], v[144:145]
	v_pk_add_f32 v[68:69], v[68:69], v[142:143]
	v_pk_add_f32 v[66:67], v[66:67], v[132:133]
	v_pk_add_f32 v[64:65], v[64:65], v[130:131]
	s_waitcnt vmcnt(7)
	v_pk_add_f32 v[70:71], v[70:71], v[152:153]
	v_pk_add_f32 v[68:69], v[68:69], v[150:151]
	v_pk_add_f32 v[66:67], v[66:67], v[140:141]
	v_pk_add_f32 v[64:65], v[64:65], v[138:139]
	s_waitcnt vmcnt(5)
; DI void phase_normmod(ArgsP a, int tb_, int l, int which, bool first, bool addp, bool ctx0, bool copyh, int MR, int vcu, int G) {
;     ...
;         if (addp && m >= ML) { const f32x4* pp = (const f32x4*)((const float*)(a->ws + A_PART) + (size_t)(m - ML) * D) + lane; s = 0.f;
; #pragma unroll
;             for (int jh = 0; jh < 2; ++jh) { f32x4 pv[2][8];
; #pragma unroll
;                 for (int jj = 0; jj < 2; ++jj)
; #pragma unroll
;                     for (int p = 0; p < 8; ++p) pv[jj][p] = pp[(size_t)p * MC * (D / 4) + 64 * (2 * jh + jj)];
;                 __builtin_amdgcn_sched_barrier(0);
; #pragma unroll
;                 for (int jj = 0; jj < 2; ++jj) { const int j = 2 * jh + jj;
; #pragma unroll
;                     for (int p = 0; p < 8; ++p) v[j] = v[j] + pv[jj][p];
;                     s += (v[j].x * v[j].x + v[j].y * v[j].y) + (v[j].z * v[j].z + v[j].w * v[j].w); } }
;             float* hrow = hc + (size_t)(m - ML) * D;
; #pragma unroll
;             for (int j = 0; j < 4; ++j) ((f32x4*)hrow + lane)[64 * j] = v[j]; }
	v_pk_add_f32 v[70:71], v[70:71], v[160:161]
	v_pk_add_f32 v[68:69], v[68:69], v[158:159]
	v_pk_add_f32 v[66:67], v[66:67], v[148:149]
	v_pk_add_f32 v[64:65], v[64:65], v[146:147]
	s_waitcnt vmcnt(3)
	v_pk_add_f32 v[70:71], v[70:71], v[168:169]
	v_pk_add_f32 v[68:69], v[68:69], v[166:167]
	v_pk_add_f32 v[66:67], v[66:67], v[156:157]
	v_pk_add_f32 v[64:65], v[64:65], v[154:155]
	s_waitcnt vmcnt(1)
	v_pk_add_f32 v[70:71], v[70:71], v[176:177]
	v_pk_add_f32 v[68:69], v[68:69], v[174:175]
	v_pk_add_f32 v[66:67], v[66:67], v[164:165]
	v_pk_add_f32 v[64:65], v[64:65], v[162:163]
	v_pk_mul_f32 v[96:97], v[70:71], v[70:71]
	v_pk_mul_f32 v[98:99], v[68:69], v[68:69]
	v_pk_add_f32 v[66:67], v[66:67], v[172:173]
	v_pk_add_f32 v[64:65], v[64:65], v[170:171]
	v_pk_mov_b32 v[126:127], v[98:99], v[96:97] op_sel:[1,0]
	v_mov_b32_e32 v99, v97
	s_waitcnt vmcnt(0)
	v_pk_add_f32 v[66:67], v[66:67], v[180:181]
	v_pk_add_f32 v[64:65], v[64:65], v[178:179]
	v_pk_add_f32 v[96:97], v[126:127], v[98:99]
	v_pk_mul_f32 v[98:99], v[66:67], v[66:67]
	v_pk_mul_f32 v[122:123], v[64:65], v[64:65]
	s_nop 0
	v_pk_mov_b32 v[124:125], v[122:123], v[98:99] op_sel:[1,0]
	v_mov_b32_e32 v123, v99
	v_pk_add_f32 v[98:99], v[124:125], v[122:123]
	global_load_dwordx4 v[122:125], v[102:103], off offset:2048
	global_load_dwordx4 v[126:129], v[100:101], off offset:2048
	global_load_dwordx4 v[130:133], v[104:105], off offset:2048
	global_load_dwordx4 v[134:137], v[106:107], off offset:2048
	global_load_dwordx4 v[138:141], v[108:109], off offset:2048
	global_load_dwordx4 v[142:145], v[110:111], off offset:2048
	global_load_dwordx4 v[146:149], v[112:113], off offset:2048
	global_load_dwordx4 v[150:153], v[114:115], off offset:2048
	global_load_dwordx4 v[154:157], v[102:103], off offset:3072
	s_nop 0
	global_load_dwordx4 v[100:103], v[100:101], off offset:3072
	s_nop 0
	global_load_dwordx4 v[158:161], v[104:105], off offset:3072
	s_nop 0
	global_load_dwordx4 v[104:107], v[106:107], off offset:3072
	s_nop 0
	global_load_dwordx4 v[162:165], v[108:109], off offset:3072
	s_nop 0
	global_load_dwordx4 v[108:111], v[110:111], off offset:3072
	s_nop 0
	global_load_dwordx4 v[166:169], v[112:113], off offset:3072
	s_nop 0
	global_load_dwordx4 v[112:115], v[114:115], off offset:3072
	s_waitcnt vmcnt(7)
	v_pk_add_f32 v[48:49], v[154:155], v[48:49]
	v_pk_add_f32 v[78:79], v[124:125], v[78:79]
	s_waitcnt vmcnt(6)
	v_pk_add_f32 v[48:49], v[48:49], v[100:101]
	v_pk_add_f32 v[76:77], v[122:123], v[76:77]
	s_waitcnt vmcnt(5)
	v_pk_add_f32 v[48:49], v[48:49], v[158:159]
	v_pk_add_f32 v[78:79], v[78:79], v[128:129]
	v_pk_add_f32 v[76:77], v[76:77], v[126:127]
	v_pk_add_f32 v[50:51], v[156:157], v[50:51]
	s_waitcnt vmcnt(4)
	v_pk_add_f32 v[48:49], v[48:49], v[104:105]
	v_pk_add_f32 v[78:79], v[78:79], v[132:133]
	v_pk_add_f32 v[76:77], v[76:77], v[130:131]
	v_pk_add_f32 v[50:51], v[50:51], v[102:103]
	s_waitcnt vmcnt(3)
	v_pk_add_f32 v[48:49], v[48:49], v[162:163]
	v_pk_add_f32 v[78:79], v[78:79], v[136:137]
	v_pk_add_f32 v[76:77], v[76:77], v[134:135]
	v_pk_add_f32 v[50:51], v[50:51], v[160:161]
	s_waitcnt vmcnt(2)
	v_pk_add_f32 v[48:49], v[48:49], v[108:109]
	v_pk_add_f32 v[78:79], v[78:79], v[140:141]
	v_pk_add_f32 v[76:77], v[76:77], v[138:139]
	v_pk_add_f32 v[50:51], v[50:51], v[106:107]
	s_waitcnt vmcnt(1)
	v_pk_add_f32 v[48:49], v[48:49], v[166:167]
	v_pk_add_f32 v[78:79], v[78:79], v[144:145]
	v_pk_add_f32 v[76:77], v[76:77], v[142:143]
	v_pk_add_f32 v[50:51], v[50:51], v[164:165]
	s_waitcnt vmcnt(0)
	v_pk_add_f32 v[48:49], v[48:49], v[112:113]
	v_pk_add_f32 v[78:79], v[78:79], v[148:149]
	v_pk_add_f32 v[76:77], v[76:77], v[146:147]
	v_pk_add_f32 v[50:51], v[50:51], v[110:111]
	v_mul_f32_e32 v100, v48, v48
	v_mul_f32_e32 v101, v49, v49
	v_pk_add_f32 v[96:97], v[96:97], v[96:97] op_sel:[0,1] op_sel_hi:[1,0]
	v_pk_add_f32 v[98:99], v[98:99], v[98:99] op_sel:[0,1] op_sel_hi:[1,0]
	v_pk_add_f32 v[78:79], v[78:79], v[152:153]
	v_pk_add_f32 v[76:77], v[76:77], v[150:151]
	v_pk_add_f32 v[50:51], v[50:51], v[168:169]
	v_mov_b32_e32 v97, v100
	v_mov_b32_e32 v99, v101
	v_pk_add_f32 v[50:51], v[50:51], v[114:115]
	v_pk_add_f32 v[96:97], v[96:97], v[98:99]
	v_mul_f32_e32 v98, v77, v77
	v_mul_f32_e32 v100, v79, v79
	v_mul_f32_e32 v102, v50, v50
	v_mul_f32_e32 v103, v51, v51
	v_pk_fma_f32 v[98:99], v[76:77], v[76:77], v[98:99] op_sel_hi:[1,1,0]
	v_pk_fma_f32 v[100:101], v[78:79], v[78:79], v[100:101] op_sel_hi:[1,1,0]
	v_mov_b32_e32 v99, v102
	v_mov_b32_e32 v101, v103
	v_pk_add_f32 v[98:99], v[98:99], v[100:101]
	v_lshl_add_u64 v[94:95], v[86:87], 0, v[94:95]
	v_pk_add_f32 v[96:97], v[96:97], v[98:99]
	global_store_dwordx4 v[94:95], v[68:71], off
	global_store_dwordx4 v[94:95], v[64:67], off offset:1024
	global_store_dwordx4 v[94:95], v[76:79], off offset:2048
	global_store_dwordx4 v[94:95], v[48:51], off offset:3072
	v_add_f32_e32 v95, v96, v97
	s_branch .LBB0_731

; DI unsigned cvtpk(float lo, float hi) { f32x2_t v = {lo, hi}; bf16x2_t b = __builtin_convertvector(v, bf16x2_t); return __builtin_bit_cast(unsigned, b); }
; DI void phase_normmod(ArgsP a, int tb_, int l, int which, bool first, bool addp, bool ctx0, bool copyh, int MR, int vcu, int G) {
;     ...
;         for (int j = 0; j < 4; ++j) { gv[j] = gp[64 * j]; sv[j] = sh[64 * j]; cv[j] = scp[64 * j] + 1.f; }
;     ...
;         const float r = rsqrtf(wave_sum(s, lane) * (1.f / D) + EPS);
;         u32x2* o = (u32x2*)(U + (size_t)m * D) + lane;
; #pragma unroll
;         for (int j = 0; j < 4; ++j) { const f32x4 y = v[j] * r * gv[j]; const f32x4 u = y * cv[j] + sv[j]; u32x2 w; w.x = cvtpk(u.x, u.y); w.y = cvtpk(u.z, u.w); o[64 * j] = w; }
.LBB0_1913:
	s_or_b64 exec, exec, s[20:21]
	v_readlane_b32 s4, v255, 31
	v_readlane_b32 s5, v255, 32
	s_lshl_b32 s14, s2, 3
	s_lshl_b64 s[4:5], s[4:5], 2
	s_waitcnt lgkmcnt(0)
	s_add_u32 s4, s16, s4
	s_addc_u32 s5, s17, s5
	v_readlane_b32 s16, v255, 33
	v_readlane_b32 s17, v255, 34
	s_lshl_b64 s[16:17], s[16:17], 2
	s_add_u32 s2, s10, s16
	s_addc_u32 s7, s11, s17
	s_add_u32 s16, s2, 0x106000
	v_lshlrev_b32_e32 v1, 2, v2
	s_addc_u32 s17, s7, 0
	v_xor_b32_e32 v120, 4, v1
	v_xor_b32_e32 v121, 8, v1
	v_xor_b32_e32 v122, 16, v1
	v_xor_b32_e32 v123, 32, v1
	v_xor_b32_e32 v124, 64, v1
	v_xor_b32_e32 v125, 0x80, v1
	v_ashrrev_i32_e32 v1, 31, v0
	s_ashr_i32 s7, s6, 31
	s_add_i32 s2, s6, s14
	v_lshlrev_b32_e32 v188, 4, v2
	v_lshlrev_b32_e32 v90, 3, v2
	v_lshl_add_u64 v[2:3], v[0:1], 0, s[6:7]
	v_add_u32_e32 v0, s2, v0
	v_ashrrev_i32_e32 v1, 31, v0
	v_lshl_add_u64 v[84:85], s[4:5], 0, v[188:189]
	v_lshl_add_u64 v[4:5], s[10:11], 0, v[188:189]
	s_mov_b64 s[4:5], 0x14a00000
	v_lshlrev_b64 v[2:3], 11, v[2:3]
	s_ashr_i32 s15, s14, 31
	v_lshlrev_b64 v[0:1], 11, v[0:1]
	v_lshl_add_u64 v[86:87], v[4:5], 0, s[4:5]
	v_lshl_add_u64 v[88:89], s[18:19], 0, v[188:189]
	v_mov_b32_e32 v91, v189
	v_lshl_add_u64 v[92:93], s[10:11], 0, v[2:3]
	s_lshl_b64 s[10:11], s[14:15], 11
	v_lshl_add_u64 v[94:95], s[8:9], 0, v[0:1]
	s_mov_b64 s[18:19], 0
	s_waitcnt vmcnt(0)
	s_branch .LBB0_1915
.LBB0_1914:
	s_or_b64 exec, exec, s[8:9]
	s_waitcnt vmcnt(5)
	v_pk_add_f32 v[98:99], v[76:77], 1.0 op_sel_hi:[1,0]
	v_pk_add_f32 v[76:77], v[66:67], 1.0 op_sel_hi:[1,0]
	s_waitcnt vmcnt(4)
	v_pk_add_f32 v[66:67], v[72:73], 1.0 op_sel_hi:[1,0]
	v_pk_add_f32 v[82:83], v[78:79], 1.0 op_sel_hi:[1,0]
	v_pk_add_f32 v[78:79], v[64:65], 1.0 op_sel_hi:[1,0]
	s_mov_b32 s2, 0xa00000
	v_pk_add_f32 v[70:71], v[70:71], 1.0 op_sel_hi:[1,0]
	v_pk_add_f32 v[68:69], v[68:69], 1.0 op_sel_hi:[1,0]
	v_pk_add_f32 v[64:65], v[74:75], 1.0 op_sel_hi:[1,0]
	s_and_b64 s[4:5], exec, s[6:7]
	s_or_b64 s[18:19], s[4:5], s[18:19]
	v_lshl_add_u64 v[92:93], v[92:93], 0, s[10:11]
	v_lshl_add_u64 v[94:95], v[94:95], 0, s[10:11]
	v_mov_b32_e32 v80, v126
	v_add_f32_dpp v72, v81, v81 quad_perm:[1,0,3,2] row_mask:0xf bank_mask:0xf
	s_nop 1
	v_add_f32_dpp v72, v72, v72 quad_perm:[2,3,0,1] row_mask:0xf bank_mask:0xf
	s_nop 1
	v_add_f32_dpp v72, v72, v72 row_half_mirror row_mask:0xf bank_mask:0xf
	s_nop 1
	v_add_f32_dpp v72, v72, v72 row_mirror row_mask:0xf bank_mask:0xf
	s_nop 1
	v_add_f32_dpp v72, v72, v72 row_bcast:15 row_mask:0xa bank_mask:0xf
	s_nop 1
	v_add_f32_dpp v72, v72, v72 row_bcast:31 row_mask:0xc bank_mask:0xf
	s_nop 0
	v_readlane_b32 vcc_lo, v72, 63
	s_nop 1
	v_mov_b32_e32 v72, vcc_lo
	v_fmamk_f32 v72, v72, 0x3a800000, v230
	v_cmp_gt_f32_e32 vcc, s76, v72
	v_mul_f32_e32 v73, 0x4b800000, v72
	s_nop 0
	v_cndmask_b32_e32 v72, v72, v73, vcc
	v_rsq_f32_e32 v72, v72
	s_nop 0
	v_mul_f32_e32 v73, 0x45800000, v72
	v_cndmask_b32_e32 v72, v72, v73, vcc
	v_pk_mul_f32 v[62:63], v[62:63], v[72:73] op_sel_hi:[1,0]
	v_pk_mul_f32 v[60:61], v[60:61], v[72:73] op_sel_hi:[1,0]
	v_pk_mul_f32 v[54:55], v[54:55], v[62:63]
	v_pk_mul_f32 v[52:53], v[52:53], v[60:61]
	v_pk_mul_f32 v[50:51], v[50:51], v[72:73] op_sel_hi:[1,0]
	v_pk_mul_f32 v[48:49], v[48:49], v[72:73] op_sel_hi:[1,0]
	v_pk_fma_f32 v[54:55], v[82:83], v[54:55], v[58:59]
	v_pk_fma_f32 v[52:53], v[98:99], v[52:53], v[56:57]
	v_pk_mul_f32 v[36:37], v[36:37], v[48:49]
	v_pk_mul_f32 v[38:39], v[38:39], v[50:51]
	v_cvt_pk_bf16_f32 v52, v52, v53
	v_cvt_pk_bf16_f32 v53, v54, v55
	v_add_co_u32_e32 v54, vcc, s2, v96
	v_pk_fma_f32 v[34:35], v[76:77], v[38:39], v[34:35]
	v_pk_fma_f32 v[32:33], v[78:79], v[36:37], v[32:33]
	v_addc_co_u32_e32 v55, vcc, 0, v97, vcc
	v_cvt_pk_bf16_f32 v32, v32, v33
	v_cvt_pk_bf16_f32 v33, v34, v35
	global_store_dwordx2 v[54:55], v[32:33], off offset:512
	v_pk_mul_f32 v[32:33], v[46:47], v[72:73] op_sel_hi:[1,0]
	v_pk_mul_f32 v[34:35], v[44:45], v[72:73] op_sel_hi:[1,0]
	v_pk_mul_f32 v[30:31], v[30:31], v[32:33]
	v_pk_mul_f32 v[28:29], v[28:29], v[34:35]
	v_pk_fma_f32 v[26:27], v[70:71], v[30:31], v[26:27]
	v_pk_fma_f32 v[24:25], v[68:69], v[28:29], v[24:25]
	s_waitcnt vmcnt(1)
	v_mov_b32_e32 v60, v0
	v_cvt_pk_bf16_f32 v24, v24, v25
	v_cvt_pk_bf16_f32 v25, v26, v27
	global_store_dwordx2 v[54:55], v[24:25], off offset:1024
	v_pk_mul_f32 v[24:25], v[42:43], v[72:73] op_sel_hi:[1,0]
	v_pk_mul_f32 v[26:27], v[40:41], v[72:73] op_sel_hi:[1,0]
	v_pk_mul_f32 v[22:23], v[22:23], v[24:25]
	v_pk_mul_f32 v[20:21], v[20:21], v[26:27]
	v_pk_fma_f32 v[18:19], v[64:65], v[22:23], v[18:19]
	v_pk_fma_f32 v[16:17], v[66:67], v[20:21], v[16:17]
	v_mov_b32_e32 v61, v1
	v_cvt_pk_bf16_f32 v16, v16, v17
	v_cvt_pk_bf16_f32 v17, v18, v19
	v_mov_b32_e32 v62, v2
	v_mov_b32_e32 v63, v3
	v_mov_b32_e32 v48, v4
	v_mov_b32_e32 v49, v5
	v_mov_b32_e32 v50, v6
	v_mov_b32_e32 v51, v7
	v_mov_b32_e32 v44, v8
	v_mov_b32_e32 v45, v9
	v_mov_b32_e32 v46, v10
	v_mov_b32_e32 v47, v11
	v_mov_b32_e32 v40, v12
	v_mov_b32_e32 v41, v13
	v_mov_b32_e32 v42, v14
	v_mov_b32_e32 v43, v15
	global_store_dwordx2 v[54:55], v[52:53], off
	global_store_dwordx2 v[54:55], v[16:17], off offset:1536
	s_andn2_b64 exec, exec, s[18:19]
	s_cbranch_execz .LBB0_1925
; DI void phase_normmod(ArgsP a, int tb_, int l, int which, bool first, bool addp, bool ctx0, bool copyh, int MR, int vcu, int G) {
;     ...
;     for (int m = gw; m < MR; m += NGW) {
;         const int br = m < ML ? (m >> 12) : 8; const bool isb = !first && m < ML;
;         f32x4 v[4]; float s = 0.f; u32x4 raw[4];
; #pragma unroll
;         for (int j = 0; j < 4; ++j) raw[j] = nraw[j];
;         { const int mn = m + NGW; if (mn < MR) NM_LOAD(mn, nraw); }
;         const f32x4* gp = (const f32x4*)g + lane; const f32x4* sh = (const f32x4*)(mod + (size_t)br * (NMOD * D) + (3 * which) * D) + lane; const f32x4* scp = (const f32x4*)(mod + (size_t)br * (NMOD * D) + (3 * which + 1) * D) + lane;
;         f32x4 gv[4], sv[4], cv[4];
; #pragma unroll
;         for (int j = 0; j < 4; ++j) { gv[j] = gp[64 * j]; sv[j] = sh[64 * j]; cv[j] = scp[64 * j] + 1.f; }
.LBB0_1915:
	v_min_i32_e32 v16, 0x8000, v80
	v_ashrrev_i32_e32 v16, 12, v16
	v_mul_hi_i32_i24_e32 v17, 0x9000, v16
	v_mul_i32_i24_e32 v16, 0x9000, v16
	v_lshl_add_u64 v[16:17], s[16:17], 0, v[16:17]
	v_lshl_add_u64 v[16:17], v[16:17], 0, v[188:189]
	s_mov_b64 s[4:5], 0x1000
	v_add_co_u32_e32 v74, vcc, s0, v16
	v_lshl_add_u64 v[72:73], v[16:17], 0, s[4:5]
	s_nop 0
	v_addc_co_u32_e32 v75, vcc, 0, v17, vcc
	global_load_dwordx4 v[52:55], v[84:85], off
	global_load_dwordx4 v[36:39], v[84:85], off offset:1024
	global_load_dwordx4 v[56:59], v[16:17], off
	global_load_dwordx4 v[32:35], v[16:17], off offset:1024
	global_load_dwordx4 v[64:67], v[72:73], off offset:1024
	global_load_dwordx4 v[68:71], v[72:73], off offset:2048
	global_load_dwordx4 v[28:31], v[84:85], off offset:2048
	global_load_dwordx4 v[20:23], v[84:85], off offset:3072
	global_load_dwordx4 v[24:27], v[16:17], off offset:2048
	s_nop 0
	global_load_dwordx4 v[16:19], v[16:17], off offset:3072
	s_nop 0
	global_load_dwordx4 v[76:79], v[74:75], off
	s_nop 0
	global_load_dwordx4 v[72:75], v[72:73], off offset:3072
	v_add_u32_e32 v126, s14, v80
	v_cmp_gt_i32_e32 vcc, s92, v126
	v_cmp_le_i32_e64 s[6:7], s92, v126
	v_mov_b32_e32 v0, v60
	v_mov_b32_e32 v1, v61
	v_mov_b32_e32 v2, v62
	v_mov_b32_e32 v3, v63
	v_mov_b32_e32 v4, v48
	v_mov_b32_e32 v5, v49
	v_mov_b32_e32 v6, v50
	v_mov_b32_e32 v7, v51
	v_mov_b32_e32 v8, v44
	v_mov_b32_e32 v9, v45
	v_mov_b32_e32 v10, v46
	v_mov_b32_e32 v11, v47
	v_mov_b32_e32 v12, v40
	v_mov_b32_e32 v13, v41
	v_mov_b32_e32 v14, v42
	v_mov_b32_e32 v15, v43
	s_and_saveexec_b64 s[8:9], vcc
	s_cbranch_execz .Lnm_skip_1915
	v_cmp_gt_i32_e32 vcc, s74, v126
	s_and_saveexec_b64 s[4:5], vcc
	s_xor_b64 s[20:21], exec, s[4:5]
	s_cbranch_execz .LBB0_1918
	v_lshl_add_u64 v[2:3], v[94:95], 0, v[90:91]
	global_load_dwordx2 v[0:1], v[2:3], off
	global_load_dwordx2 v[4:5], v[2:3], off offset:512
	global_load_dwordx2 v[8:9], v[2:3], off offset:1024
	global_load_dwordx2 v[12:13], v[2:3], off offset:1536

; DI void phase_normmod(ArgsP a, int tb_, int l, int which, bool first, bool addp, bool ctx0, bool copyh, int MR, int vcu, int G) {
;     ...
;         if (copyh && isb) { u32x2* c = (u32x2*)(hcopy + (size_t)m * D) + lane;
; #pragma unroll
;             for (int j = 0; j < 4; ++j) c[64 * j] = (u32x2){raw[j].x, raw[j].y}; }
.LBB0_1921:
	s_or_b64 exec, exec, s[8:9]
	v_cmp_gt_i32_e64 s[8:9], s74, v80
	s_and_b64 s[4:5], s[34:35], s[8:9]
	v_lshl_add_u64 v[96:97], v[92:93], 0, v[90:91]
	s_and_saveexec_b64 s[20:21], s[4:5]
	s_cbranch_execz .LBB0_1923
	v_add_co_u32_e32 v82, vcc, 0x18a00000, v96
	s_nop 1
	v_addc_co_u32_e32 v83, vcc, 0, v97, vcc
	global_store_dwordx2 v[82:83], v[60:61], off
	global_store_dwordx2 v[82:83], v[48:49], off offset:512
	global_store_dwordx2 v[82:83], v[44:45], off offset:1024
	global_store_dwordx2 v[82:83], v[40:41], off offset:1536
